# retention head-decay constant via scalar select instead of per-unit log1pf expansion; RG-LRU softplus(-lam) table computed once per phase into LDS; lru gate-weight loads issued back to back
# speedup vs baseline: 1.0237x; 1.0034x over previous
.LBB0_643:
	s_or_b64 exec, exec, s[42:43]
	s_waitcnt vmcnt(0)
	s_mov_b32 s100, 0xbc8102b3
	s_cmp_eq_u32 s6, 0
	s_cselect_b32 s100, 0xbd020aec, s100
	s_mov_b32 s101, 0xbb80402b
	s_cmp_eq_u32 s6, 2
	s_cselect_b32 s101, 0xbc0080ac, s101
	s_cmp_lt_u32 s6, 2
	s_cselect_b32 s100, s100, s101
	v_mov_b32_e32 v34, s100
	v_ashrrev_i32_e32 v27, 6, v56
	v_and_b32_e32 v29, 15, v56
	v_and_b32_e32 v31, 48, v56
	v_and_b32_e32 v30, -16, v44
	s_waitcnt lgkmcnt(0)
	s_barrier
	v_lshlrev_b32_e32 v4, 1, v27
	v_and_b32_e32 v28, 2, v4
	v_mul_u32_u24_e32 v4, 0x68, v29
	v_lshlrev_b32_e32 v4, 1, v4
	v_add3_u32 v8, 0, v4, v31
	v_mad_u64_u32 v[24:25], s[26:27], v30, s79, v[8:9]
	ds_read_b128 v[4:7], v24 offset:24576
	v_mad_u32_u24 v25, v28, s25, v8
	ds_read_b128 v[8:11], v25 offset:37888
	ds_read_b128 v[12:15], v24 offset:24640
	s_waitcnt lgkmcnt(1)
	v_mfma_f32_16x16x32_bf16 v[4:7], v[4:7], v[8:11], 0
	ds_read_b128 v[16:19], v25 offset:37952
	ds_read_b128 v[20:23], v24 offset:24704
	v_lshrrev_b32_e32 v33, 2, v56
	v_and_b32_e32 v33, 12, v33
	v_or_b32_e32 v30, v33, v30
	v_lshl_or_b32 v28, v28, 4, v29
	s_waitcnt lgkmcnt(1)
	v_mfma_f32_16x16x32_bf16 v[4:7], v[12:15], v[16:19], v[4:7]
	v_sub_u32_e32 v12, v30, v28
	ds_read_b128 v[8:11], v25 offset:38016
	v_sub_u32_e32 v13, 0, v12
	v_max_i32_e32 v12, v12, v13
	v_cvt_f32_u32_e32 v12, v12
	s_waitcnt lgkmcnt(0)
	v_mfma_f32_16x16x32_bf16 v[4:7], v[20:23], v[8:11], v[4:7]
	v_or_b32_e32 v35, 2, v30
	v_or_b32_e32 v26, 1, v30
	v_sub_u32_e32 v9, v26, v28
	v_mul_f32_e32 v8, v34, v12
	v_sub_u32_e32 v10, 0, v9
	v_mul_f32_e32 v8, 0x3fb8aa3b, v8
	v_max_i32_e32 v9, v9, v10
	v_exp_f32_e32 v8, v8
	v_cvt_f32_u32_e32 v9, v9
	v_lshl_add_u32 v10, v28, 1, s62
	v_mul_lo_u32 v32, v30, s21
	v_mul_f32_e32 v4, v8, v4
	v_mul_f32_e32 v8, v34, v9
	v_mul_f32_e32 v8, 0x3fb8aa3b, v8
	v_exp_f32_e32 v8, v8
	v_cvt_pk_bf16_f32 v4, v4, s0
	v_add_u32_e32 v9, v10, v32
	ds_write_b16 v9, v4
	v_mul_f32_e32 v4, v8, v5
	v_sub_u32_e32 v5, v35, v28
	v_sub_u32_e32 v8, 0, v5
	v_max_i32_e32 v5, v5, v8
	v_cvt_f32_u32_e32 v5, v5
	v_or_b32_e32 v37, 3, v30
	v_sub_u32_e32 v9, v37, v28
	v_sub_u32_e32 v11, 0, v9
	v_mul_f32_e32 v5, v34, v5
	v_mul_f32_e32 v5, 0x3fb8aa3b, v5
	v_max_i32_e32 v9, v9, v11
	v_exp_f32_e32 v5, v5
	v_cvt_f32_u32_e32 v9, v9
	v_add_u32_e32 v36, 0x90, v32
	v_cvt_pk_bf16_f32 v4, v4, s0
	v_add_u32_e32 v8, v10, v36
	ds_write_b16 v8, v4
	v_mul_f32_e32 v4, v5, v6
	v_mul_f32_e32 v5, v34, v9
	v_mul_f32_e32 v5, 0x3fb8aa3b, v5
	v_exp_f32_e32 v5, v5
	v_add_u32_e32 v38, 0x120, v32
	v_cvt_pk_bf16_f32 v4, v4, s0
	v_add_u32_e32 v6, v10, v38
	ds_write_b16 v6, v4
	v_mul_f32_e32 v4, v5, v7
	v_add_u32_e32 v39, 0x1b0, v32
	v_cvt_pk_bf16_f32 v4, v4, s0
	v_add_u32_e32 v5, v10, v39
	ds_write_b16 v5, v4
	ds_read_b128 v[4:7], v24 offset:24576
	ds_read_b128 v[8:11], v25 offset:41216
	ds_read_b128 v[12:15], v24 offset:24640
	ds_read_b128 v[16:19], v24 offset:24704
	s_waitcnt lgkmcnt(2)
	v_mfma_f32_16x16x32_bf16 v[4:7], v[4:7], v[8:11], 0
	ds_read_b128 v[8:11], v25 offset:41280
	ds_read_b128 v[20:23], v25 offset:41344
	v_readlane_b32 s12, v255, 2
	s_waitcnt lgkmcnt(1)
	v_mfma_f32_16x16x32_bf16 v[4:7], v[12:15], v[8:11], v[4:7]
	v_or_b32_e32 v8, 16, v28
	v_sub_u32_e32 v9, v30, v8
	v_sub_u32_e32 v10, 0, v9
	v_max_i32_e32 v9, v9, v10
	v_sub_u32_e32 v11, v26, v8
	v_cvt_f32_u32_e32 v9, v9
	v_sub_u32_e32 v12, 0, v11
	v_max_i32_e32 v11, v11, v12
	v_cvt_f32_u32_e32 v11, v11
	v_mul_f32_e32 v9, v34, v9
	v_mul_f32_e32 v9, 0x3fb8aa3b, v9
	v_sub_u32_e32 v12, v35, v8
	s_waitcnt lgkmcnt(0)
	v_mfma_f32_16x16x32_bf16 v[4:7], v[16:19], v[20:23], v[4:7]
	v_exp_f32_e32 v9, v9
	v_mul_f32_e32 v11, v34, v11
	v_sub_u32_e32 v13, 0, v12
	v_mul_f32_e32 v11, 0x3fb8aa3b, v11
	v_max_i32_e32 v12, v12, v13
	v_exp_f32_e32 v11, v11
	v_cvt_f32_u32_e32 v12, v12
	v_lshl_add_u32 v10, v8, 1, s62
	v_mul_f32_e32 v4, v9, v4
	v_cvt_pk_bf16_f32 v4, v4, s0
	v_add_u32_e32 v9, v10, v32
	v_sub_u32_e32 v8, v37, v8
	ds_write_b16 v9, v4
	v_mul_f32_e32 v4, v11, v5
	v_mul_f32_e32 v5, v34, v12
	v_sub_u32_e32 v9, 0, v8
	v_mul_f32_e32 v5, 0x3fb8aa3b, v5
	v_max_i32_e32 v8, v8, v9
	v_exp_f32_e32 v5, v5
	v_cvt_f32_u32_e32 v8, v8
	v_cvt_pk_bf16_f32 v4, v4, s0
	v_add_u32_e32 v9, v10, v36
	ds_write_b16 v9, v4
	v_mul_f32_e32 v4, v5, v6
	v_mul_f32_e32 v5, v34, v8
	v_mul_f32_e32 v5, 0x3fb8aa3b, v5
	v_exp_f32_e32 v5, v5
	v_cvt_pk_bf16_f32 v4, v4, s0
	v_add_u32_e32 v6, v10, v38
	ds_write_b16 v6, v4
	v_mul_f32_e32 v4, v5, v7
	v_cvt_pk_bf16_f32 v4, v4, s0
	v_add_u32_e32 v5, v10, v39
	ds_write_b16 v5, v4
	v_mul_u32_u24_e32 v4, 0x48, v29
	v_lshlrev_b32_e32 v4, 1, v4
	v_add3_u32 v28, s62, v4, v31
	v_add3_u32 v30, 0, v4, v31
	v_lshrrev_b32_e32 v4, 31, v56
	v_lshl_add_u32 v35, v27, 1, v27
	v_add_u32_e32 v4, v27, v4
	v_ashrrev_i32_e32 v31, 1, v4
	v_mul_hi_i32 v4, v35, s18
	s_waitcnt lgkmcnt(0)
	s_barrier
	v_lshrrev_b32_e32 v5, 31, v4
	v_mad_u64_u32 v[12:13], s[26:27], v31, s7, v[28:29]
	v_add_u32_e32 v8, v4, v5
	ds_read_b128 v[4:7], v12
	v_mul_lo_u32 v8, v8, 6
	v_sub_u32_e32 v36, v35, v8
	v_mad_i32_i24 v16, v36, s7, v30
	ds_read_b128 v[8:11], v16 offset:51200
	v_lshl_add_u32 v32, v29, 6, v30
	v_mad_u64_u32 v[24:25], s[26:27], v31, s25, v[32:33]
	ds_read_b128 v[12:15], v12 offset:64
	ds_read_b128 v[16:19], v16 offset:51264
	s_waitcnt lgkmcnt(2)
	v_mfma_f32_16x16x32_bf16 v[4:7], v[4:7], v[8:11], 0
	ds_read_b128 v[8:11], v24 offset:24576
	v_mad_i32_i24 v25, v36, s25, v32
	ds_read_b128 v[20:23], v25 offset:65024
	s_waitcnt lgkmcnt(2)
	v_mfma_f32_16x16x32_bf16 v[4:7], v[12:15], v[16:19], v[4:7]
	ds_read_b128 v[12:15], v24 offset:24640
	ds_read_b128 v[16:19], v24 offset:24704
	v_lshl_add_u32 v37, v29, 2, s12
	s_waitcnt lgkmcnt(2)
	v_mfma_f32_16x16x32_bf16 v[8:11], v[8:11], v[20:23], 0
	ds_read_b128 v[20:23], v25 offset:65088
	ds_read_b128 v[24:27], v25 offset:65152
	s_waitcnt lgkmcnt(1)
	v_mfma_f32_16x16x32_bf16 v[8:11], v[12:15], v[20:23], v[8:11]
	v_lshl_or_b32 v12, v31, 4, v33
	v_or_b32_e32 v13, 1, v12
	v_cvt_f32_i32_e32 v13, v13
	s_waitcnt lgkmcnt(0)
	v_mfma_f32_16x16x32_bf16 v[8:11], v[16:19], v[24:27], v[8:11]
	v_lshlrev_b32_e32 v14, 6, v36
	v_or_b32_e32 v15, 2, v12
	v_mul_f32_e32 v13, v34, v13
	v_mul_f32_e32 v13, 0x3fb8aa3b, v13
	v_exp_f32_e32 v13, v13
	v_cvt_f32_i32_e32 v15, v15
	s_nop 1
	v_fma_f32 v4, v13, v8, v4
	v_mul_lo_u32 v8, v12, s63
	v_add3_u32 v8, v37, v14, v8
	v_or_b32_e32 v14, 3, v12
	v_add_u32_e32 v12, 4, v12
	v_cvt_f32_i32_e32 v14, v14
	v_cvt_f32_i32_e32 v12, v12
	v_mul_f32_e32 v13, v34, v15
	v_mul_f32_e32 v13, 0x3fb8aa3b, v13
	v_mul_f32_e32 v14, v34, v14
	v_mul_f32_e32 v12, v34, v12
	v_exp_f32_e32 v13, v13
	v_mul_f32_e32 v14, 0x3fb8aa3b, v14
	v_mul_f32_e32 v12, 0x3fb8aa3b, v12
	v_exp_f32_e32 v14, v14
	v_exp_f32_e32 v12, v12
	v_fma_f32 v5, v13, v9, v5
	ds_write2_b32 v8, v4, v5 offset1:100
	v_fma_f32 v4, v14, v10, v6
	v_fmac_f32_e32 v7, v12, v11
	v_add_u32_e32 v5, 0x200, v8
	ds_write2_b32 v5, v4, v7 offset0:72 offset1:172
	v_add_u32_e32 v4, 1, v35
	v_mul_hi_i32 v5, v4, s18
	v_lshrrev_b32_e32 v6, 31, v5
	v_add_u32_e32 v29, v5, v6
	v_mul_lo_u32 v5, v29, 6
	v_mad_u64_u32 v[8:9], s[26:27], v29, s7, v[28:29]
	v_sub_u32_e32 v31, v4, v5
	ds_read_b128 v[4:7], v8
	v_mad_u64_u32 v[16:17], s[26:27], v31, s7, v[30:31]
	v_mad_u64_u32 v[24:25], s[26:27], v29, s25, v[32:33]
	ds_read_b128 v[8:11], v8 offset:64
	ds_read_b128 v[12:15], v16 offset:51200
	ds_read_b128 v[16:19], v16 offset:51264
	ds_read_b128 v[20:23], v24 offset:24576
	v_mad_u64_u32 v[26:27], s[26:27], v31, s25, v[32:33]
	s_waitcnt lgkmcnt(2)
	v_mfma_f32_16x16x32_bf16 v[4:7], v[4:7], v[12:15], 0
	ds_read_b128 v[12:15], v26 offset:65024
	s_waitcnt lgkmcnt(2)
	v_mfma_f32_16x16x32_bf16 v[4:7], v[8:11], v[16:19], v[4:7]
	ds_read_b128 v[8:11], v24 offset:24640
	ds_read_b128 v[16:19], v24 offset:24704
	s_waitcnt lgkmcnt(2)
	v_mfma_f32_16x16x32_bf16 v[12:15], v[20:23], v[12:15], 0
	ds_read_b128 v[20:23], v26 offset:65088
	ds_read_b128 v[24:27], v26 offset:65152
	s_waitcnt lgkmcnt(1)
	v_mfma_f32_16x16x32_bf16 v[8:11], v[8:11], v[20:23], v[12:15]
	s_nop 3
	v_lshl_or_b32 v12, v29, 4, v33
	v_or_b32_e32 v13, 1, v12
	v_cvt_f32_i32_e32 v13, v13
	s_waitcnt lgkmcnt(0)
	v_mfma_f32_16x16x32_bf16 v[8:11], v[16:19], v[24:27], v[8:11]
	v_lshlrev_b32_e32 v14, 6, v31
	v_or_b32_e32 v15, 2, v12
	v_mul_f32_e32 v13, v34, v13
	v_mul_f32_e32 v13, 0x3fb8aa3b, v13
	v_exp_f32_e32 v13, v13
	v_cvt_f32_i32_e32 v15, v15
	s_nop 1
	v_fma_f32 v4, v13, v8, v4
	v_mul_lo_u32 v8, v12, s63
	v_add3_u32 v8, v37, v14, v8
	v_or_b32_e32 v14, 3, v12
	v_add_u32_e32 v12, 4, v12
	v_cvt_f32_i32_e32 v14, v14
	v_cvt_f32_i32_e32 v12, v12
	v_mul_f32_e32 v13, v34, v15
	v_mul_f32_e32 v13, 0x3fb8aa3b, v13
	v_mul_f32_e32 v14, v34, v14
	v_mul_f32_e32 v12, v34, v12
	v_exp_f32_e32 v13, v13
	v_mul_f32_e32 v14, 0x3fb8aa3b, v14
	v_mul_f32_e32 v12, 0x3fb8aa3b, v12
	v_exp_f32_e32 v14, v14
	v_exp_f32_e32 v12, v12
	v_fma_f32 v5, v13, v9, v5
	ds_write2_b32 v8, v4, v5 offset1:100
	v_fma_f32 v4, v14, v10, v6
	v_fmac_f32_e32 v7, v12, v11
	v_add_u32_e32 v5, 0x200, v8
	v_add_u32_e32 v8, 2, v35
	ds_write2_b32 v5, v4, v7 offset0:72 offset1:172
	v_mul_hi_i32 v4, v8, s18
	v_lshrrev_b32_e32 v5, 31, v4
	v_add_u32_e32 v35, v4, v5
	v_mad_u64_u32 v[12:13], s[26:27], v35, s7, v[28:29]
	ds_read_b128 v[4:7], v12
	v_mul_lo_u32 v9, v35, 6
	v_sub_u32_e32 v36, v8, v9
	v_mad_u64_u32 v[16:17], s[26:27], v36, s7, v[30:31]
	ds_read_b128 v[8:11], v16 offset:51200
	ds_read_b128 v[12:15], v12 offset:64
	ds_read_b128 v[16:19], v16 offset:51264
	v_mad_u64_u32 v[28:29], s[26:27], v35, s25, v[32:33]
	s_waitcnt lgkmcnt(2)
	v_mfma_f32_16x16x32_bf16 v[4:7], v[4:7], v[8:11], 0
	ds_read_b128 v[8:11], v28 offset:24576
	v_mad_u64_u32 v[30:31], s[26:27], v36, s25, v[32:33]
	ds_read_b128 v[20:23], v30 offset:65024
	ds_read_b128 v[24:27], v28 offset:24640
	s_waitcnt lgkmcnt(3)
	v_mfma_f32_16x16x32_bf16 v[4:7], v[12:15], v[16:19], v[4:7]
	ds_read_b128 v[12:15], v30 offset:65088
	ds_read_b128 v[16:19], v28 offset:24704
	s_add_u32 s26, s50, s60
	s_addc_u32 s27, s51, 0
	s_waitcnt lgkmcnt(3)
	v_mfma_f32_16x16x32_bf16 v[8:11], v[8:11], v[20:23], 0
	ds_read_b128 v[20:23], v30 offset:65152
	s_lshl_b32 s6, s10, 2
	s_add_u32 s10, s91, s6
	s_waitcnt lgkmcnt(2)
	v_mfma_f32_16x16x32_bf16 v[8:11], v[24:27], v[12:15], v[8:11]
	v_lshl_or_b32 v12, v35, 4, v33
	v_or_b32_e32 v13, 1, v12
	v_cvt_f32_i32_e32 v13, v13
	s_waitcnt lgkmcnt(0)
	v_mfma_f32_16x16x32_bf16 v[8:11], v[16:19], v[20:23], v[8:11]
	v_lshlrev_b32_e32 v14, 6, v36
	v_or_b32_e32 v15, 2, v12
	v_mul_f32_e32 v13, v34, v13
	v_mul_f32_e32 v13, 0x3fb8aa3b, v13
	v_exp_f32_e32 v13, v13
	v_cvt_f32_i32_e32 v15, v15
	v_lshlrev_b32_e32 v24, 2, v45
	s_addc_u32 s11, s92, 0
	v_fma_f32 v4, v13, v8, v4
	v_mul_lo_u32 v8, v12, s63
	v_add3_u32 v8, v37, v14, v8
	v_or_b32_e32 v14, 3, v12
	v_add_u32_e32 v12, 4, v12
	v_cvt_f32_i32_e32 v14, v14
	v_cvt_f32_i32_e32 v12, v12
	v_mul_f32_e32 v13, v34, v15
	v_mul_f32_e32 v13, 0x3fb8aa3b, v13
	v_mul_f32_e32 v14, v34, v14
	v_mul_f32_e32 v12, v34, v12
	v_exp_f32_e32 v13, v13
	v_mul_f32_e32 v14, 0x3fb8aa3b, v14
	v_mul_f32_e32 v12, 0x3fb8aa3b, v12
	v_exp_f32_e32 v14, v14
	v_exp_f32_e32 v12, v12
	v_fma_f32 v5, v13, v9, v5
	ds_write2_b32 v8, v4, v5 offset1:100
	v_fma_f32 v4, v14, v10, v6
	v_fmac_f32_e32 v7, v12, v11
	v_add_u32_e32 v5, 0x200, v8
	ds_write2_b32 v5, v4, v7 offset0:72 offset1:172
	v_mul_lo_u32 v4, v44, s63
	v_and_b32_e32 v5, 64, v188
	v_add3_u32 v12, s12, v4, v24
	v_xor_b32_e32 v4, 1, v188
	v_add_u32_e32 v5, 64, v5
	v_cmp_lt_i32_e32 vcc, v4, v5
	s_waitcnt lgkmcnt(0)
	s_barrier
	v_lshlrev_b32_e32 v30, 16, v0
	v_cndmask_b32_e32 v4, v188, v4, vcc
	v_lshlrev_b32_e32 v50, 2, v4
	v_xor_b32_e32 v4, 2, v188
	v_cmp_lt_i32_e32 vcc, v4, v5
	v_and_b32_e32 v31, 0xffff0000, v0
	v_mul_f32_e32 v0, 0xbfb8aa3b, v30
	v_cndmask_b32_e32 v4, v188, v4, vcc
	v_lshlrev_b32_e32 v51, 2, v4
	v_xor_b32_e32 v4, 4, v188
	v_cmp_lt_i32_e32 vcc, v4, v5
	v_exp_f32_e32 v0, v0
	s_nop 0
	v_cndmask_b32_e32 v4, v188, v4, vcc
	v_lshlrev_b32_e32 v52, 2, v4
	v_lshlrev_b64 v[4:5], 11, v[42:43]
	v_lshl_add_u64 v[4:5], s[26:27], 0, v[4:5]
	v_lshl_add_u64 v[28:29], v[4:5], 0, v[140:141]
	ds_read_b128 v[4:7], v12
	ds_read_b128 v[8:11], v12 offset:16
	ds_read_b128 v[12:15], v12 offset:32
	v_add_f32_e32 v0, 1.0, v0
	v_rcp_f32_e32 v32, v0
	s_waitcnt lgkmcnt(2)
	v_add_f32_e32 v16, 0, v4
	v_add_f32_e32 v33, v16, v5
	global_load_dwordx4 v[16:19], v24, s[10:11] offset:32
	global_load_dwordx4 v[20:23], v24, s[10:11] offset:16
	s_nop 0
	global_load_dwordx4 v[24:27], v24, s[10:11]
	v_add_f32_e32 v33, v33, v6
	v_add_f32_e32 v33, v33, v7
	s_waitcnt lgkmcnt(1)
	v_add_f32_e32 v33, v33, v8
	v_add_f32_e32 v33, v33, v9
	v_add_f32_e32 v33, v33, v10
	v_add_f32_e32 v33, v33, v11
	s_waitcnt lgkmcnt(0)
	v_add_f32_e32 v33, v33, v12
	v_add_f32_e32 v33, v33, v13
	v_add_f32_e32 v33, v33, v14
	v_add_f32_e32 v34, v33, v15
	ds_bpermute_b32 v35, v50, v34
	v_mul_f32_e32 v0, 0xbfb8aa3b, v31
	v_exp_f32_e32 v0, v0
	s_waitcnt lgkmcnt(0)
	v_add_f32_e32 v34, v34, v35
	ds_bpermute_b32 v35, v51, v34
	v_add_f32_e32 v0, 1.0, v0
	v_rcp_f32_e32 v33, v0
	v_lshlrev_b32_e32 v0, 16, v1
	v_mul_f32_e32 v36, 0xbfb8aa3b, v0
	s_waitcnt lgkmcnt(0)
	v_add_f32_e32 v38, v34, v35
	ds_bpermute_b32 v39, v52, v38
	v_and_b32_e32 v1, 0xffff0000, v1
	v_exp_f32_e32 v36, v36
	v_mul_f32_e32 v37, 0xbfb8aa3b, v1
	v_exp_f32_e32 v37, v37
	v_pk_mul_f32 v[30:31], v[32:33], v[30:31]
	v_add_f32_e32 v34, 1.0, v36
	s_waitcnt lgkmcnt(0)
	v_add_f32_e32 v36, v38, v39
	v_mul_f32_e32 v36, 0x3c2aaaab, v36
	v_pk_add_f32 v[4:5], v[4:5], v[36:37] op_sel_hi:[1,0] neg_lo:[0,1] neg_hi:[0,1]
	v_pk_add_f32 v[6:7], v[6:7], v[36:37] op_sel_hi:[1,0] neg_lo:[0,1] neg_hi:[0,1]
	v_pk_mul_f32 v[38:39], v[4:5], v[4:5]
	v_pk_mul_f32 v[42:43], v[6:7], v[6:7]
	v_add_f32_e32 v38, v38, v39
	v_pk_add_f32 v[8:9], v[8:9], v[36:37] op_sel_hi:[1,0] neg_lo:[0,1] neg_hi:[0,1]
	v_add_f32_e32 v38, v42, v38
	v_pk_mul_f32 v[44:45], v[8:9], v[8:9]
	v_add_f32_e32 v38, v43, v38
	v_pk_add_f32 v[10:11], v[10:11], v[36:37] op_sel_hi:[1,0] neg_lo:[0,1] neg_hi:[0,1]
	v_add_f32_e32 v38, v44, v38
	v_pk_mul_f32 v[46:47], v[10:11], v[10:11]
	v_add_f32_e32 v38, v45, v38
	v_pk_add_f32 v[12:13], v[12:13], v[36:37] op_sel_hi:[1,0] neg_lo:[0,1] neg_hi:[0,1]
	v_add_f32_e32 v38, v46, v38
	v_pk_mul_f32 v[48:49], v[12:13], v[12:13]
	v_add_f32_e32 v38, v47, v38
	v_pk_add_f32 v[14:15], v[14:15], v[36:37] op_sel_hi:[1,0] neg_lo:[0,1] neg_hi:[0,1]
	v_add_f32_e32 v38, v48, v38
	v_add_f32_e32 v35, 1.0, v37
	v_pk_mul_f32 v[36:37], v[14:15], v[14:15]
	v_add_f32_e32 v38, v49, v38
	v_add_f32_e32 v36, v36, v38
	v_add_f32_e32 v36, v37, v36
	ds_bpermute_b32 v37, v50, v36
	v_rcp_f32_e32 v34, v34
	v_rcp_f32_e32 v35, v35
	s_nop 0
	v_pk_mul_f32 v[32:33], v[34:35], v[0:1]
	v_lshlrev_b32_e32 v0, 16, v2
	v_and_b32_e32 v1, 0xffff0000, v2
	s_waitcnt lgkmcnt(0)
	v_add_f32_e32 v2, v36, v37
	ds_bpermute_b32 v34, v51, v2
	v_mul_f32_e32 v35, 0xbfb8aa3b, v0
	v_mul_f32_e32 v36, 0xbfb8aa3b, v1
	v_exp_f32_e32 v35, v35
	v_exp_f32_e32 v36, v36
	s_waitcnt lgkmcnt(0)
	v_add_f32_e32 v2, v2, v34
	ds_bpermute_b32 v37, v52, v2
	v_add_f32_e32 v34, 1.0, v35
	v_add_f32_e32 v35, 1.0, v36
	v_rcp_f32_e32 v34, v34
	v_rcp_f32_e32 v35, v35
	s_waitcnt lgkmcnt(0)
	v_add_f32_e32 v2, v2, v37
	v_fmamk_f32 v2, v2, 0x3c2aaaab, v187
	v_mul_f32_e32 v36, 0x4b800000, v2
	v_cmp_gt_f32_e32 vcc, s78, v2
	v_pk_mul_f32 v[34:35], v[34:35], v[0:1]
	v_and_b32_e32 v37, 0xffff0000, v3
	v_cndmask_b32_e32 v2, v2, v36, vcc
	v_rsq_f32_e32 v2, v2
	v_lshlrev_b32_e32 v36, 16, v3
	v_mul_f32_e32 v0, 0x45800000, v2
	v_cndmask_b32_e32 v38, v2, v0, vcc
	v_pk_mul_f32 v[0:1], v[4:5], v[38:39] op_sel_hi:[1,0]
	v_mul_f32_e32 v4, 0xbfb8aa3b, v36
	v_mul_f32_e32 v5, 0xbfb8aa3b, v37
	v_exp_f32_e32 v4, v4
	v_exp_f32_e32 v5, v5
	v_pk_mul_f32 v[2:3], v[6:7], v[38:39] op_sel_hi:[1,0]
	s_waitcnt vmcnt(0)
	v_pk_mul_f32 v[0:1], v[24:25], v[0:1]
	v_add_f32_e32 v4, 1.0, v4
	v_add_f32_e32 v5, 1.0, v5
	v_rcp_f32_e32 v4, v4
	v_rcp_f32_e32 v5, v5
	v_pk_mul_f32 v[2:3], v[26:27], v[2:3]
	v_pk_mul_f32 v[0:1], v[30:31], v[0:1]
	v_pk_mul_f32 v[2:3], v[32:33], v[2:3]
	v_cvt_pk_bf16_f32 v0, v0, v1
	v_cvt_pk_bf16_f32 v1, v2, v3
	v_pk_mul_f32 v[2:3], v[8:9], v[38:39] op_sel_hi:[1,0]
	v_pk_mul_f32 v[6:7], v[10:11], v[38:39] op_sel_hi:[1,0]
	v_pk_mul_f32 v[2:3], v[20:21], v[2:3]
	v_pk_mul_f32 v[6:7], v[22:23], v[6:7]
	v_pk_mul_f32 v[4:5], v[4:5], v[36:37]
	v_pk_mul_f32 v[2:3], v[34:35], v[2:3]
	v_pk_mul_f32 v[4:5], v[4:5], v[6:7]
	v_lshlrev_b32_e32 v6, 16, v40
	v_cvt_pk_bf16_f32 v2, v2, v3
	v_and_b32_e32 v7, 0xffff0000, v40
	v_mul_f32_e32 v3, 0xbfb8aa3b, v6
	v_exp_f32_e32 v8, v3
	v_mul_f32_e32 v3, 0xbfb8aa3b, v7
	v_exp_f32_e32 v9, v3
	v_cvt_pk_bf16_f32 v3, v4, v5
	v_add_f32_e32 v4, 1.0, v8
	v_rcp_f32_e32 v4, v4
	v_add_f32_e32 v5, 1.0, v9
	v_rcp_f32_e32 v5, v5
	global_store_dwordx4 v[28:29], v[0:3], off
	s_nop 1
	v_pk_mul_f32 v[2:3], v[4:5], v[6:7]
	v_lshlrev_b32_e32 v4, 16, v41
	v_and_b32_e32 v5, 0xffff0000, v41
	v_mul_f32_e32 v6, 0xbfb8aa3b, v4
	v_mul_f32_e32 v7, 0xbfb8aa3b, v5
	v_exp_f32_e32 v6, v6
	v_exp_f32_e32 v7, v7
	v_pk_mul_f32 v[0:1], v[12:13], v[38:39] op_sel_hi:[1,0]
	s_nop 0
	v_pk_mul_f32 v[0:1], v[16:17], v[0:1]
	s_nop 0
	v_pk_mul_f32 v[0:1], v[2:3], v[0:1]
	v_add_f32_e32 v2, 1.0, v6
	v_add_f32_e32 v3, 1.0, v7
	v_rcp_f32_e32 v2, v2
	v_rcp_f32_e32 v3, v3
	v_pk_mul_f32 v[6:7], v[14:15], v[38:39] op_sel_hi:[1,0]
	v_cvt_pk_bf16_f32 v0, v0, v1
	v_pk_mul_f32 v[6:7], v[18:19], v[6:7]
	v_pk_mul_f32 v[2:3], v[2:3], v[4:5]
	s_nop 0
	v_pk_mul_f32 v[2:3], v[2:3], v[6:7]
	s_nop 0
	v_cvt_pk_bf16_f32 v1, v2, v3
	global_store_dwordx2 v[28:29], v[0:1], off offset:16
	s_waitcnt lgkmcnt(0)
	s_barrier

.LBB0_693:
	s_waitcnt lgkmcnt(0)
	v_readlane_b32 s92, v255, 24
	v_readlane_b32 s90, v255, 22
	v_readlane_b32 s93, v255, 25
	s_andn2_b64 vcc, exec, s[86:87]
	v_readlane_b32 s91, v255, 23
	v_readlane_b32 s93, v255, 26
	s_cbranch_vccnz .LBB0_803
	v_readlane_b32 s10, v252, 29
	v_readlane_b32 s11, v252, 30
	s_andn2_b64 vcc, exec, s[10:11]
	s_cbranch_vccnz .LBB0_757
	s_add_u32 s72, s54, 0x1b690000
	s_addc_u32 s73, s55, 0
	v_readlane_b32 s26, v255, 27
	s_load_dwordx2 s[10:11], s[34:35], 0xf8
	s_nop 0
	s_load_dwordx2 s[34:35], s[58:59], 0xf8
	s_load_dwordx2 s[42:43], s[82:83], 0x60
	s_load_dwordx2 s[44:45], s[30:31], 0x68
	s_load_dwordx2 s[46:47], s[74:75], 0x78
	s_load_dwordx2 s[50:51], s[70:71], 0x88
	s_nop 0
	s_load_dwordx2 s[52:53], s[52:53], 0x90
	v_readlane_b32 s27, v255, 28
	s_add_u32 s30, s26, 0x1d790000
	s_addc_u32 s31, s27, 0
	v_readlane_b32 s26, v255, 29
	v_readlane_b32 s27, v255, 30
	s_add_u32 s26, s26, 0x1d810000
	s_addc_u32 s27, s27, 0
	s_waitcnt lgkmcnt(0)
	s_add_u32 s74, s10, 0x3280000
	s_addc_u32 s75, s11, 0
	s_add_u32 s82, s34, 0x3288000
	s_addc_u32 s83, s35, 0
	s_lshl_b32 s6, s38, 2
	s_add_u32 s34, s42, s6
	s_addc_u32 s35, s43, 0
	s_and_b64 s[10:11], s[76:77], exec
	s_cselect_b32 s6, 0, 0x400
	s_add_u32 s38, s44, s6
	s_addc_u32 s39, s45, 0
	s_add_u32 s44, s46, s6
	s_addc_u32 s45, s47, 0
	s_add_u32 s46, s50, s6
	s_addc_u32 s47, s51, 0
	s_add_u32 s50, s52, s6
	s_addc_u32 s51, s53, 0
	s_mov_b32 s76, s2
	v_and_b32_e32 v104, 0xff, v186
	v_lshlrev_b32_e32 v104, 2, v104
	global_load_dword v20, v104, s[50:51]
	s_waitcnt vmcnt(0)
	s_mov_b32 s6, 0xbfb8aa3b
	v_mul_f32_e32 v21, 0xbfb8aa3b, v20
	v_fma_f32 v22, v20, s6, -v21
	v_rndne_f32_e32 v23, v21
	v_fmac_f32_e32 v22, 0xb2a5705f, v20
	v_sub_f32_e32 v21, v21, v23
	v_add_f32_e32 v21, v21, v22
	v_exp_f32_e32 v21, v21
	v_cvt_i32_f32_e32 v22, v23
	s_mov_b32 s6, 0x42ce8ed0
	v_cmp_nlt_f32_e32 vcc, s6, v20
	s_mov_b32 s6, 0xc2b17218
	v_ldexp_f32 v21, v21, v22
	v_cndmask_b32_e32 v21, 0, v21, vcc
	v_cmp_ngt_f32_e32 vcc, s6, v20
	s_nop 1
	v_cndmask_b32_e32 v22, v202, v21, vcc
	v_add_f32_e32 v23, 1.0, v22
	v_add_f32_e32 v20, -1.0, v23
	v_sub_f32_e32 v21, v20, v23
	v_add_f32_e32 v21, 1.0, v21
	v_sub_f32_e32 v20, v22, v20
	v_add_f32_e32 v24, v20, v21
	v_frexp_mant_f32_e32 v20, v23
	v_cmp_gt_f32_e32 vcc, s14, v20
	v_cvt_f64_f32_e32 v[20:21], v23
	v_frexp_exp_i32_f64_e32 v20, v[20:21]
	v_subbrev_co_u32_e32 v20, vcc, 0, v20, vcc
	v_sub_u32_e32 v21, 0, v20
	v_ldexp_f32 v23, v23, v21
	v_ldexp_f32 v21, v24, v21
	v_add_f32_e32 v24, -1.0, v23
	v_add_f32_e32 v25, 1.0, v24
	v_sub_f32_e32 v25, v23, v25
	v_add_f32_e32 v25, v21, v25
	v_add_f32_e32 v26, v24, v25
	v_sub_f32_e32 v24, v24, v26
	v_add_f32_e32 v24, v25, v24
	v_add_f32_e32 v25, 1.0, v23
	v_add_f32_e32 v27, -1.0, v25
	v_sub_f32_e32 v23, v23, v27
	v_add_f32_e32 v21, v21, v23
	v_add_f32_e32 v23, v25, v21
	v_sub_f32_e32 v25, v25, v23
	v_add_f32_e32 v21, v21, v25
	v_rcp_f32_e32 v25, v23
	v_cvt_f32_i32_e32 v20, v20
	v_cmp_neq_f32_e32 vcc, s17, v22
	v_mul_f32_e32 v27, v26, v25
	v_mul_f32_e32 v28, v23, v27
	v_fma_f32 v29, v27, v23, -v28
	v_fmac_f32_e32 v29, v27, v21
	v_add_f32_e32 v30, v28, v29
	v_sub_f32_e32 v31, v26, v30
	v_sub_f32_e32 v26, v26, v31
	v_sub_f32_e32 v28, v30, v28
	v_sub_f32_e32 v26, v26, v30
	v_add_f32_e32 v24, v24, v26
	v_sub_f32_e32 v26, v28, v29
	v_add_f32_e32 v24, v26, v24
	v_add_f32_e32 v26, v31, v24
	v_mul_f32_e32 v28, v25, v26
	v_mul_f32_e32 v29, v23, v28
	v_fma_f32 v23, v28, v23, -v29
	v_fmac_f32_e32 v23, v28, v21
	v_sub_f32_e32 v21, v31, v26
	v_add_f32_e32 v21, v24, v21
	v_add_f32_e32 v24, v29, v23
	v_sub_f32_e32 v30, v26, v24
	v_sub_f32_e32 v26, v26, v30
	v_sub_f32_e32 v29, v24, v29
	v_sub_f32_e32 v24, v26, v24
	v_add_f32_e32 v21, v21, v24
	v_sub_f32_e32 v23, v29, v23
	v_add_f32_e32 v21, v23, v21
	v_add_f32_e32 v23, v27, v28
	v_add_f32_e32 v21, v30, v21
	v_sub_f32_e32 v24, v23, v27
	v_mul_f32_e32 v21, v25, v21
	v_sub_f32_e32 v24, v28, v24
	v_add_f32_e32 v21, v24, v21
	v_mul_f32_e32 v27, 0x3f317218, v20
	v_add_f32_e32 v24, v23, v21
	v_fma_f32 v28, v20, s15, -v27
	v_mul_f32_e32 v25, v24, v24
	v_fmac_f32_e32 v28, 0xb102e308, v20
	v_sub_f32_e32 v20, v24, v23
	v_fmamk_f32 v26, v25, 0x3e9b6dac, v189
	v_sub_f32_e32 v20, v21, v20
	v_add_f32_e32 v21, v27, v28
	v_fmaak_f32 v26, v25, v26, 0x3f2aaada
	v_sub_f32_e32 v23, v21, v27
	v_ldexp_f32 v27, v24, 1
	v_mul_f32_e32 v24, v24, v25
	v_mul_f32_e32 v24, v24, v26
	v_add_f32_e32 v25, v27, v24
	v_sub_f32_e32 v26, v25, v27
	v_ldexp_f32 v20, v20, 1
	v_sub_f32_e32 v24, v24, v26
	v_add_f32_e32 v20, v20, v24
	v_add_f32_e32 v24, v25, v20
	v_sub_f32_e32 v25, v24, v25
	v_sub_f32_e32 v20, v20, v25
	v_add_f32_e32 v25, v21, v24
	v_sub_f32_e32 v26, v25, v21
	v_sub_f32_e32 v27, v25, v26
	v_sub_f32_e32 v23, v28, v23
	v_sub_f32_e32 v21, v21, v27
	v_sub_f32_e32 v24, v24, v26
	v_add_f32_e32 v21, v24, v21
	v_add_f32_e32 v24, v23, v20
	v_sub_f32_e32 v26, v24, v23
	v_sub_f32_e32 v27, v24, v26
	v_sub_f32_e32 v23, v23, v27
	v_sub_f32_e32 v20, v20, v26
	v_add_f32_e32 v21, v24, v21
	v_add_f32_e32 v20, v20, v23
	v_add_f32_e32 v23, v25, v21
	v_sub_f32_e32 v24, v23, v25
	v_sub_f32_e32 v21, v21, v24
	v_add_f32_e32 v20, v20, v21
	v_add_f32_e32 v20, v23, v20
	v_cndmask_b32_e32 v20, v202, v20, vcc
	v_cmp_lt_f32_e64 vcc, |v22|, s16
	s_nop 1
	v_cndmask_b32_e32 v22, v20, v22, vcc
	v_add_u32_e32 v104, 0x23000, v104
	ds_write_b32 v104, v22
	s_waitcnt lgkmcnt(0)
	s_barrier
	s_branch .LBB0_698

.LBB0_709:
	s_or_b64 exec, exec, s[42:43]
	s_movk_i32 s12, 0x400
	v_lshlrev_b32_e32 v0, 1, v10
	v_bfe_u32 v16, v9, 9, 1
	v_cmp_gt_u32_e32 vcc, s12, v9
	v_mov_b32_e32 v17, s83
	v_mov_b32_e32 v18, s75
	v_mov_b32_e32 v19, s82
	v_mov_b32_e32 v20, s74
	s_lshl_b32 s6, s6, 14
	v_bfe_u32 v8, v9, 3, 6
	v_and_b32_e32 v4, 0x70, v0
	v_cndmask_b32_e32 v1, v17, v18, vcc
	v_cndmask_b32_e32 v0, v19, v20, vcc
	v_lshl_or_b32 v140, v16, 13, s6
	v_lshl_add_u64 v[0:1], v[0:1], 0, v[140:141]
	v_lshlrev_b32_e32 v12, 7, v8
	v_mov_b32_e32 v13, v141
	v_lshl_add_u64 v[0:1], v[0:1], 0, v[12:13]
	v_mov_b32_e32 v5, v141
	v_lshl_add_u64 v[0:1], v[0:1], 0, v[4:5]
	global_load_dwordx4 v[108:111], v[0:1], off
	v_readlane_b32 s10, v255, 3
	v_lshrrev_b32_e32 v7, 3, v9
	v_add_u32_e32 v11, 0x200, v9
	v_add_u32_e32 v6, s10, v4
	v_mad_u64_u32 v[124:125], s[10:11], v7, s21, v[6:7]
	v_cmp_gt_u32_e32 vcc, s12, v11
	v_lshrrev_b32_e32 v7, 3, v11
	s_mov_b32 s19, 0xfffffc0
	v_and_or_b32 v7, v7, s19, v8
	s_mov_b32 s58, 0
	v_lshlrev_b32_e32 v2, 4, v11
	v_and_b32_e32 v2, 0x2000, v2
	v_cndmask_b32_e32 v1, v17, v18, vcc
	v_cndmask_b32_e32 v0, v19, v20, vcc
	v_or_b32_e32 v2, s6, v2
	v_mov_b32_e32 v3, v141
	v_lshl_add_u64 v[0:1], v[0:1], 0, v[2:3]
	v_lshl_add_u64 v[0:1], v[0:1], 0, v[12:13]
	v_lshl_add_u64 v[0:1], v[0:1], 0, v[4:5]
	global_load_dwordx4 v[112:115], v[0:1], off
	v_mad_u64_u32 v[126:127], s[10:11], v7, s21, v[6:7]
	s_movk_i32 s10, 0xfbff
	s_nop 0
	v_cmp_lt_u32_e32 vcc, s10, v9
	v_add_u32_e32 v7, 0x400, v9
	v_lshrrev_b32_e32 v7, 9, v7
	s_mov_b32 s10, 0x3ffffe
	v_and_or_b32 v7, v7, s10, v16
	v_lshl_or_b32 v7, v7, 6, v8
	v_cndmask_b32_e32 v1, v17, v18, vcc
	v_cndmask_b32_e32 v0, v19, v20, vcc
	v_lshl_add_u64 v[0:1], v[0:1], 0, v[140:141]
	v_lshl_add_u64 v[0:1], v[0:1], 0, v[12:13]
	v_lshl_add_u64 v[0:1], v[0:1], 0, v[4:5]
	global_load_dwordx4 v[116:119], v[0:1], off
	v_mad_u64_u32 v[128:129], s[10:11], v7, s21, v[6:7]
	v_add_u32_e32 v7, 0x600, v9
	v_cmp_gt_u32_e32 vcc, s12, v7
	v_lshlrev_b32_e32 v2, 4, v7
	v_and_b32_e32 v2, 0x2000, v2
	v_cndmask_b32_e32 v1, v17, v18, vcc
	v_cndmask_b32_e32 v0, v19, v20, vcc
	v_or_b32_e32 v140, s6, v2
	v_lshl_add_u64 v[0:1], v[0:1], 0, v[140:141]
	v_lshl_add_u64 v[0:1], v[0:1], 0, v[12:13]
	v_lshl_add_u64 v[0:1], v[0:1], 0, v[4:5]
	global_load_dwordx4 v[120:123], v[0:1], off
	v_lshrrev_b32_e32 v4, 3, v7
	v_and_or_b32 v4, v4, s19, v8
	v_and_b32_e32 v13, 0x7f, v9
	v_mad_u64_u32 v[4:5], s[10:11], v4, s21, v[6:7]
	v_or_b32_e32 v8, s87, v13
	v_ashrrev_i32_e32 v12, 7, v9
	v_lshlrev_b32_e32 v5, 1, v13
	v_lshl_add_u32 v6, v9, 1, s8
	v_lshlrev_b32_e32 v7, 8, v12
	v_add3_u32 v7, s8, v7, v5
	s_movk_i32 s6, 0x110
	s_add_i32 s10, 0, 0x10000
	s_waitcnt vmcnt(3)
	ds_write_b128 v124, v[108:111]
	s_waitcnt vmcnt(2)
	ds_write_b128 v126, v[112:115]
	s_waitcnt vmcnt(1)
	ds_write_b128 v128, v[116:119]
	s_waitcnt vmcnt(0)
	ds_write_b128 v4, v[120:123]
	v_lshlrev_b32_e32 v1, 2, v8
	global_load_dword v4, v1, s[34:35]
	global_load_dword v3, v1, s[34:35] offset:1024
	global_load_dword v2, v1, s[34:35] offset:2048
	global_load_dword v0, v1, s[34:35] offset:3072
	s_nop 0
	global_load_dword v1, v1, s[38:39]
	s_waitcnt lgkmcnt(0)
	s_barrier
	ds_read_u16 v6, v6
	ds_read_u16 v14, v7 offset:256
	s_waitcnt lgkmcnt(1)
	v_lshlrev_b32_e32 v6, 16, v6
	s_waitcnt lgkmcnt(0)
	v_lshlrev_b32_e32 v14, 16, v14
	s_waitcnt vmcnt(0)
	v_fma_f32 v6, v4, v6, v1
	v_fmac_f32_e32 v6, v3, v14
	ds_read_u16 v14, v7 offset:512
	ds_read_u16 v7, v7 offset:768
	s_waitcnt lgkmcnt(1)
	v_lshlrev_b32_e32 v14, 16, v14
	v_fmac_f32_e32 v6, v2, v14
	s_waitcnt lgkmcnt(0)
	v_lshlrev_b32_e32 v7, 16, v7
	v_fmac_f32_e32 v6, v0, v7
	v_lshl_add_u32 v7, v9, 2, 0
	ds_write_b32 v7, v6
	v_cvt_pk_bf16_f32 v7, v6, s0
	v_mul_lo_u32 v6, v12, s6
	v_add3_u32 v6, s10, v5, v6
	ds_write_b16 v6, v7
	v_add_u32_e32 v7, 4, v12
	v_lshl_or_b32 v14, v7, 7, v13
	v_lshl_add_u32 v15, v14, 1, s8
	v_lshlrev_b32_e32 v7, 8, v7
	ds_read_u16 v15, v15
	v_add3_u32 v7, s8, v7, v5
	ds_read_u16 v16, v7 offset:256
	s_waitcnt lgkmcnt(1)
	v_lshlrev_b32_e32 v15, 16, v15
	v_fma_f32 v15, v4, v15, v1
	s_waitcnt lgkmcnt(0)
	v_lshlrev_b32_e32 v16, 16, v16
	v_fmac_f32_e32 v15, v3, v16
	ds_read_u16 v16, v7 offset:512
	ds_read_u16 v7, v7 offset:768
	s_waitcnt lgkmcnt(1)
	v_lshlrev_b32_e32 v16, 16, v16
	v_fmac_f32_e32 v15, v2, v16
	s_waitcnt lgkmcnt(0)
	v_lshlrev_b32_e32 v7, 16, v7
	v_fmac_f32_e32 v15, v0, v7
	v_lshl_add_u32 v7, v14, 2, 0
	ds_write_b32 v7, v15
	v_cvt_pk_bf16_f32 v7, v15, s0
	ds_write_b16 v6, v7 offset:1088
	v_add_u32_e32 v7, 8, v12
	v_lshl_or_b32 v14, v7, 7, v13
	v_lshl_add_u32 v15, v14, 1, s8
	v_lshlrev_b32_e32 v7, 8, v7
	ds_read_u16 v15, v15
	v_add3_u32 v7, s8, v7, v5
	ds_read_u16 v16, v7 offset:256
	s_waitcnt lgkmcnt(1)
	v_lshlrev_b32_e32 v15, 16, v15
	v_fma_f32 v15, v4, v15, v1
	s_waitcnt lgkmcnt(0)
	v_lshlrev_b32_e32 v16, 16, v16
	v_fmac_f32_e32 v15, v3, v16
	ds_read_u16 v16, v7 offset:512
	ds_read_u16 v7, v7 offset:768
	s_waitcnt lgkmcnt(1)
	v_lshlrev_b32_e32 v16, 16, v16
	v_fmac_f32_e32 v15, v2, v16
	s_waitcnt lgkmcnt(0)
	v_lshlrev_b32_e32 v7, 16, v7
	v_fmac_f32_e32 v15, v0, v7
	v_lshl_add_u32 v7, v14, 2, 0
	ds_write_b32 v7, v15
	v_cvt_pk_bf16_f32 v7, v15, s0
	ds_write_b16 v6, v7 offset:2176
	v_add_u32_e32 v7, 12, v12
	v_lshl_or_b32 v14, v7, 7, v13
	v_lshl_add_u32 v15, v14, 1, s8
	v_lshlrev_b32_e32 v7, 8, v7
	ds_read_u16 v15, v15
	v_add3_u32 v7, s8, v7, v5
	ds_read_u16 v16, v7 offset:256
	s_waitcnt lgkmcnt(1)
	v_lshlrev_b32_e32 v15, 16, v15
	v_fma_f32 v15, v4, v15, v1
	s_waitcnt lgkmcnt(0)
	v_lshlrev_b32_e32 v16, 16, v16
	v_fmac_f32_e32 v15, v3, v16
	ds_read_u16 v16, v7 offset:512
	ds_read_u16 v7, v7 offset:768
	s_waitcnt lgkmcnt(1)
	v_lshlrev_b32_e32 v16, 16, v16
	v_fmac_f32_e32 v15, v2, v16
	s_waitcnt lgkmcnt(0)
	v_lshlrev_b32_e32 v7, 16, v7
	v_fmac_f32_e32 v15, v0, v7
	v_lshl_add_u32 v7, v14, 2, 0
	ds_write_b32 v7, v15
	v_cvt_pk_bf16_f32 v7, v15, s0
	ds_write_b16 v6, v7 offset:3264
	v_add_u32_e32 v7, 16, v12
	v_lshl_or_b32 v14, v7, 7, v13
	v_lshl_add_u32 v15, v14, 1, s8
	v_lshlrev_b32_e32 v7, 8, v7
	ds_read_u16 v15, v15
	v_add3_u32 v7, s8, v7, v5
	ds_read_u16 v16, v7 offset:256
	s_waitcnt lgkmcnt(1)
	v_lshlrev_b32_e32 v15, 16, v15
	v_fma_f32 v15, v4, v15, v1
	s_waitcnt lgkmcnt(0)
	v_lshlrev_b32_e32 v16, 16, v16
	v_fmac_f32_e32 v15, v3, v16
	ds_read_u16 v16, v7 offset:512
	ds_read_u16 v7, v7 offset:768
	s_waitcnt lgkmcnt(1)
	v_lshlrev_b32_e32 v16, 16, v16
	v_fmac_f32_e32 v15, v2, v16
	s_waitcnt lgkmcnt(0)
	v_lshlrev_b32_e32 v7, 16, v7
	v_fmac_f32_e32 v15, v0, v7
	v_lshl_add_u32 v7, v14, 2, 0
	ds_write_b32 v7, v15
	v_cvt_pk_bf16_f32 v7, v15, s0
	ds_write_b16 v6, v7 offset:4352
	v_add_u32_e32 v7, 20, v12
	v_lshl_or_b32 v14, v7, 7, v13
	v_lshl_add_u32 v15, v14, 1, s8
	v_lshlrev_b32_e32 v7, 8, v7
	ds_read_u16 v15, v15
	v_add3_u32 v7, s8, v7, v5
	ds_read_u16 v16, v7 offset:256
	s_waitcnt lgkmcnt(1)
	v_lshlrev_b32_e32 v15, 16, v15
	v_fma_f32 v15, v4, v15, v1
	s_waitcnt lgkmcnt(0)
	v_lshlrev_b32_e32 v16, 16, v16
	v_fmac_f32_e32 v15, v3, v16
	ds_read_u16 v16, v7 offset:512
	ds_read_u16 v7, v7 offset:768
	s_waitcnt lgkmcnt(1)
	v_lshlrev_b32_e32 v16, 16, v16
	v_fmac_f32_e32 v15, v2, v16
	s_waitcnt lgkmcnt(0)
	v_lshlrev_b32_e32 v7, 16, v7
	v_fmac_f32_e32 v15, v0, v7
	v_lshl_add_u32 v7, v14, 2, 0
	ds_write_b32 v7, v15
	v_cvt_pk_bf16_f32 v7, v15, s0
	ds_write_b16 v6, v7 offset:5440
	v_add_u32_e32 v7, 24, v12
	v_lshl_or_b32 v14, v7, 7, v13
	v_lshl_add_u32 v15, v14, 1, s8
	v_lshlrev_b32_e32 v7, 8, v7
	ds_read_u16 v15, v15
	v_add3_u32 v7, s8, v7, v5
	ds_read_u16 v16, v7 offset:256
	s_waitcnt lgkmcnt(1)
	v_lshlrev_b32_e32 v15, 16, v15
	v_fma_f32 v15, v4, v15, v1
	s_waitcnt lgkmcnt(0)
	v_lshlrev_b32_e32 v16, 16, v16
	v_fmac_f32_e32 v15, v3, v16
	ds_read_u16 v16, v7 offset:512
	ds_read_u16 v7, v7 offset:768
	s_waitcnt lgkmcnt(1)
	v_lshlrev_b32_e32 v16, 16, v16
	v_fmac_f32_e32 v15, v2, v16
	s_waitcnt lgkmcnt(0)
	v_lshlrev_b32_e32 v7, 16, v7
	v_fmac_f32_e32 v15, v0, v7
	v_lshl_add_u32 v7, v14, 2, 0
	ds_write_b32 v7, v15
	v_cvt_pk_bf16_f32 v7, v15, s0
	ds_write_b16 v6, v7 offset:6528
	v_add_u32_e32 v7, 28, v12
	v_lshl_or_b32 v14, v7, 7, v13
	v_lshl_add_u32 v15, v14, 1, s8
	v_lshlrev_b32_e32 v7, 8, v7
	ds_read_u16 v15, v15
	v_add3_u32 v7, s8, v7, v5
	ds_read_u16 v16, v7 offset:256
	s_waitcnt lgkmcnt(1)
	v_lshlrev_b32_e32 v15, 16, v15
	v_fma_f32 v15, v4, v15, v1
	s_waitcnt lgkmcnt(0)
	v_lshlrev_b32_e32 v16, 16, v16
	v_fmac_f32_e32 v15, v3, v16
	ds_read_u16 v16, v7 offset:512
	ds_read_u16 v7, v7 offset:768
	s_waitcnt lgkmcnt(1)
	v_lshlrev_b32_e32 v16, 16, v16
	v_fmac_f32_e32 v15, v2, v16
	s_waitcnt lgkmcnt(0)
	v_lshlrev_b32_e32 v7, 16, v7
	v_fmac_f32_e32 v15, v0, v7
	v_lshl_add_u32 v7, v14, 2, 0
	ds_write_b32 v7, v15
	v_cvt_pk_bf16_f32 v7, v15, s0
	ds_write_b16 v6, v7 offset:7616
	v_add_u32_e32 v7, 32, v12
	v_lshl_or_b32 v14, v7, 7, v13
	v_lshl_add_u32 v15, v14, 1, s8
	v_lshlrev_b32_e32 v7, 8, v7
	ds_read_u16 v15, v15
	v_add3_u32 v7, s8, v7, v5
	ds_read_u16 v16, v7 offset:256
	s_waitcnt lgkmcnt(1)
	v_lshlrev_b32_e32 v15, 16, v15
	v_fma_f32 v15, v4, v15, v1
	s_waitcnt lgkmcnt(0)
	v_lshlrev_b32_e32 v16, 16, v16
	v_fmac_f32_e32 v15, v3, v16
	ds_read_u16 v16, v7 offset:512
	ds_read_u16 v7, v7 offset:768
	s_waitcnt lgkmcnt(1)
	v_lshlrev_b32_e32 v16, 16, v16
	v_fmac_f32_e32 v15, v2, v16
	s_waitcnt lgkmcnt(0)
	v_lshlrev_b32_e32 v7, 16, v7
	v_fmac_f32_e32 v15, v0, v7
	v_lshl_add_u32 v7, v14, 2, 0
	ds_write_b32 v7, v15
	v_cvt_pk_bf16_f32 v7, v15, s0
	ds_write_b16 v6, v7 offset:8704
	v_add_u32_e32 v7, 36, v12
	v_lshl_or_b32 v14, v7, 7, v13
	v_lshl_add_u32 v15, v14, 1, s8
	v_lshlrev_b32_e32 v7, 8, v7
	ds_read_u16 v15, v15
	v_add3_u32 v7, s8, v7, v5
	ds_read_u16 v16, v7 offset:256
	s_waitcnt lgkmcnt(1)
	v_lshlrev_b32_e32 v15, 16, v15
	v_fma_f32 v15, v4, v15, v1
	s_waitcnt lgkmcnt(0)
	v_lshlrev_b32_e32 v16, 16, v16
	v_fmac_f32_e32 v15, v3, v16
	ds_read_u16 v16, v7 offset:512
	ds_read_u16 v7, v7 offset:768
	s_waitcnt lgkmcnt(1)
	v_lshlrev_b32_e32 v16, 16, v16
	v_fmac_f32_e32 v15, v2, v16
	s_waitcnt lgkmcnt(0)
	v_lshlrev_b32_e32 v7, 16, v7
	v_fmac_f32_e32 v15, v0, v7
	v_lshl_add_u32 v7, v14, 2, 0
	ds_write_b32 v7, v15
	v_cvt_pk_bf16_f32 v7, v15, s0
	ds_write_b16 v6, v7 offset:9792
	v_add_u32_e32 v7, 40, v12
	v_lshl_or_b32 v14, v7, 7, v13
	v_lshl_add_u32 v15, v14, 1, s8
	v_lshlrev_b32_e32 v7, 8, v7
	ds_read_u16 v15, v15
	v_add3_u32 v7, s8, v7, v5
	ds_read_u16 v16, v7 offset:256
	s_waitcnt lgkmcnt(1)
	v_lshlrev_b32_e32 v15, 16, v15
	v_fma_f32 v15, v4, v15, v1
	s_waitcnt lgkmcnt(0)
	v_lshlrev_b32_e32 v16, 16, v16
	v_fmac_f32_e32 v15, v3, v16
	ds_read_u16 v16, v7 offset:512
	ds_read_u16 v7, v7 offset:768
	s_waitcnt lgkmcnt(1)
	v_lshlrev_b32_e32 v16, 16, v16
	v_fmac_f32_e32 v15, v2, v16
	s_waitcnt lgkmcnt(0)
	v_lshlrev_b32_e32 v7, 16, v7
	v_fmac_f32_e32 v15, v0, v7
	v_lshl_add_u32 v7, v14, 2, 0
	ds_write_b32 v7, v15
	v_cvt_pk_bf16_f32 v7, v15, s0
	ds_write_b16 v6, v7 offset:10880
	v_add_u32_e32 v7, 44, v12
	v_lshl_or_b32 v14, v7, 7, v13
	v_lshl_add_u32 v15, v14, 1, s8
	v_lshlrev_b32_e32 v7, 8, v7
	ds_read_u16 v15, v15
	v_add3_u32 v7, s8, v7, v5
	ds_read_u16 v16, v7 offset:256
	s_waitcnt lgkmcnt(1)
	v_lshlrev_b32_e32 v15, 16, v15
	v_fma_f32 v15, v4, v15, v1
	s_waitcnt lgkmcnt(0)
	v_lshlrev_b32_e32 v16, 16, v16
	v_fmac_f32_e32 v15, v3, v16
	ds_read_u16 v16, v7 offset:512
	ds_read_u16 v7, v7 offset:768
	s_waitcnt lgkmcnt(1)
	v_lshlrev_b32_e32 v16, 16, v16
	v_fmac_f32_e32 v15, v2, v16
	s_waitcnt lgkmcnt(0)
	v_lshlrev_b32_e32 v7, 16, v7
	v_fmac_f32_e32 v15, v0, v7
	v_lshl_add_u32 v7, v14, 2, 0
	ds_write_b32 v7, v15
	v_cvt_pk_bf16_f32 v7, v15, s0
	ds_write_b16 v6, v7 offset:11968
	v_add_u32_e32 v7, 48, v12
	v_lshl_or_b32 v14, v7, 7, v13
	v_lshl_add_u32 v15, v14, 1, s8
	v_lshlrev_b32_e32 v7, 8, v7
	ds_read_u16 v15, v15
	v_add3_u32 v7, s8, v7, v5
	ds_read_u16 v16, v7 offset:256
	s_waitcnt lgkmcnt(1)
	v_lshlrev_b32_e32 v15, 16, v15
	v_fma_f32 v15, v4, v15, v1
	s_waitcnt lgkmcnt(0)
	v_lshlrev_b32_e32 v16, 16, v16
	v_fmac_f32_e32 v15, v3, v16
	ds_read_u16 v16, v7 offset:512
	ds_read_u16 v7, v7 offset:768
	s_waitcnt lgkmcnt(1)
	v_lshlrev_b32_e32 v16, 16, v16
	v_fmac_f32_e32 v15, v2, v16
	s_waitcnt lgkmcnt(0)
	v_lshlrev_b32_e32 v7, 16, v7
	v_fmac_f32_e32 v15, v0, v7
	v_lshl_add_u32 v7, v14, 2, 0
	ds_write_b32 v7, v15
	v_cvt_pk_bf16_f32 v7, v15, s0
	ds_write_b16 v6, v7 offset:13056
	v_add_u32_e32 v7, 52, v12
	v_lshl_or_b32 v14, v7, 7, v13
	v_lshl_add_u32 v15, v14, 1, s8
	v_lshlrev_b32_e32 v7, 8, v7
	ds_read_u16 v15, v15
	v_add3_u32 v7, s8, v7, v5
	ds_read_u16 v16, v7 offset:256
	s_waitcnt lgkmcnt(1)
	v_lshlrev_b32_e32 v15, 16, v15
	v_fma_f32 v15, v4, v15, v1
	s_waitcnt lgkmcnt(0)
	v_lshlrev_b32_e32 v16, 16, v16
	v_fmac_f32_e32 v15, v3, v16
	ds_read_u16 v16, v7 offset:512
	ds_read_u16 v7, v7 offset:768
	s_waitcnt lgkmcnt(1)
	v_lshlrev_b32_e32 v16, 16, v16
	v_fmac_f32_e32 v15, v2, v16
	s_waitcnt lgkmcnt(0)
	v_lshlrev_b32_e32 v7, 16, v7
	v_fmac_f32_e32 v15, v0, v7
	v_lshl_add_u32 v7, v14, 2, 0
	ds_write_b32 v7, v15
	v_cvt_pk_bf16_f32 v7, v15, s0
	ds_write_b16 v6, v7 offset:14144
	v_add_u32_e32 v7, 56, v12
	v_lshl_or_b32 v14, v7, 7, v13
	v_lshl_add_u32 v15, v14, 1, s8
	v_lshlrev_b32_e32 v7, 8, v7
	ds_read_u16 v15, v15
	v_add3_u32 v7, s8, v7, v5
	ds_read_u16 v16, v7 offset:256
	s_waitcnt lgkmcnt(1)
	v_lshlrev_b32_e32 v15, 16, v15
	v_fma_f32 v15, v4, v15, v1
	s_waitcnt lgkmcnt(0)
	v_lshlrev_b32_e32 v16, 16, v16
	v_fmac_f32_e32 v15, v3, v16
	ds_read_u16 v16, v7 offset:512
	ds_read_u16 v7, v7 offset:768
	s_waitcnt lgkmcnt(1)
	v_lshlrev_b32_e32 v16, 16, v16
	v_fmac_f32_e32 v15, v2, v16
	s_waitcnt lgkmcnt(0)
	v_lshlrev_b32_e32 v7, 16, v7
	v_fmac_f32_e32 v15, v0, v7
	v_lshl_add_u32 v7, v14, 2, 0
	ds_write_b32 v7, v15
	v_cvt_pk_bf16_f32 v7, v15, s0
	ds_write_b16 v6, v7 offset:15232
	v_add_u32_e32 v7, 60, v12
	v_lshl_or_b32 v14, v7, 7, v13
	v_lshl_add_u32 v15, v14, 1, s8
	ds_read_u16 v15, v15
	s_waitcnt lgkmcnt(0)
	v_lshlrev_b32_e32 v15, 16, v15
	v_fmac_f32_e32 v1, v4, v15
	v_lshlrev_b32_e32 v4, 8, v7
	v_add3_u32 v4, s8, v4, v5
	ds_read_u16 v5, v4 offset:256
	s_waitcnt lgkmcnt(0)
	v_lshlrev_b32_e32 v5, 16, v5
	v_fmac_f32_e32 v1, v3, v5
	ds_read_u16 v3, v4 offset:512
	s_waitcnt lgkmcnt(0)
	v_lshlrev_b32_e32 v3, 16, v3
	v_fmac_f32_e32 v1, v2, v3
	ds_read_u16 v2, v4 offset:768
	v_mov_b32_e32 v4, s10
	s_waitcnt lgkmcnt(0)
	v_lshlrev_b32_e32 v2, 16, v2
	v_fmac_f32_e32 v1, v0, v2
	v_lshl_add_u32 v0, v14, 2, 0
	ds_write_b32 v0, v1
	v_cvt_pk_bf16_f32 v0, v1, s0
	v_lshrrev_b32_e32 v2, 2, v9
	ds_write_b16 v6, v0 offset:16320
	v_and_b32_e32 v0, 15, v9
	v_and_b32_e32 v2, 48, v2
	v_bfe_u32 v1, v9, 4, 2
	v_or_b32_e32 v3, v2, v0
	v_mad_u32_u24 v3, v3, s6, v4
	v_ashrrev_i32_e32 v4, 2, v9
	v_lshlrev_b32_e32 v7, 4, v1
	v_lshlrev_b32_e32 v1, 9, v1
	v_and_b32_e32 v5, 0xffffffc0, v4
	v_lshl_or_b32 v1, v2, 7, v1
	v_add_u32_e32 v1, v1, v5
	v_or_b32_e32 v1, v1, v0
	s_waitcnt lgkmcnt(0)
	s_barrier
	v_lshlrev_b32_e32 v16, 2, v1
	v_lshrrev_b32_e32 v1, 6, v4
	s_movk_i32 s6, 0x2400
	v_lshlrev_b32_e32 v6, 1, v5
	v_add3_u32 v15, s87, v5, v0
	v_mul_lo_u32 v1, v1, s6
	v_mul_u32_u24_e32 v0, 0x90, v0
	v_add3_u32 v14, v3, v6, v7
	v_add3_u32 v17, v1, v0, v7
.LBB0_710:
	v_add_u32_e32 v104, s58, v15
	v_ashrrev_i32_e32 v105, 31, v104
	v_lshlrev_b64 v[104:105], 2, v[104:105]
	v_lshl_add_u64 v[106:107], s[44:45], 0, v[104:105]
	global_load_dword v100, v[106:107], off
	v_lshl_add_u64 v[106:107], s[46:47], 0, v[104:105]
	global_load_dword v101, v[106:107], off
	v_add_u32_e32 v106, 0x23000, v104
	ds_read_b32 v102, v106
	v_add_u32_e32 v26, 0, v17
	v_add_u32_e32 v4, 0x18c00, v26
	v_add_u32_e32 v18, 0x1d400, v26
	ds_read_b128 v[0:3], v14
	ds_read_b128 v[4:7], v4
	ds_read_b128 v[18:21], v18
	v_add_u32_e32 v22, 0x18c40, v26
	v_add_u32_e32 v26, 0x1d440, v26
	s_waitcnt lgkmcnt(1)
	v_mfma_f32_16x16x32_bf16 v[4:7], v[0:3], v[4:7], 0
	ds_read_b128 v[22:25], v22
	ds_read_b128 v[26:29], v26
	s_mov_b32 s6, 0xbfb8aa3b
	s_waitcnt lgkmcnt(2)
	v_mfma_f32_16x16x32_bf16 v[0:3], v[0:3], v[18:21], 0
	ds_read_b128 v[18:21], v14 offset:64
	v_add_u32_e32 v17, 0x900, v17
	s_waitcnt lgkmcnt(0)
	v_mfma_f32_16x16x32_bf16 v[4:7], v[18:21], v[22:25], v[4:7]
	v_mfma_f32_16x16x32_bf16 v[0:3], v[18:21], v[26:29], v[0:3]
	s_add_i32 s58, s58, 16
	s_cmp_eq_u32 s58, 64
	s_nop 3
	s_waitcnt vmcnt(0)
	v_mov_b32_e32 v20, v100
	v_mov_b32_e32 v19, v101
	v_mul_f32_e32 v18, 0xc1000000, v102
	s_waitcnt vmcnt(1)
	v_add_f32_e32 v4, v4, v20
	v_mul_f32_e32 v4, 0xbfb8aa3b, v4
	v_exp_f32_e32 v4, v4
	s_waitcnt vmcnt(0)
	v_add_f32_e32 v0, v0, v19
	v_mul_f32_e32 v0, 0xbfb8aa3b, v0
	v_exp_f32_e32 v0, v0
	v_add_f32_e32 v4, 1.0, v4
	v_div_scale_f32 v21, s[10:11], v4, v4, 1.0
	v_rcp_f32_e32 v22, v21
	v_add_f32_e32 v0, 1.0, v0
	v_add_f32_e32 v5, v5, v20
	v_mul_f32_e32 v5, 0xbfb8aa3b, v5
	v_fma_f32 v23, -v21, v22, 1.0
	v_fmac_f32_e32 v22, v23, v22
	v_div_scale_f32 v23, vcc, 1.0, v4, 1.0
	v_mul_f32_e32 v24, v23, v22
	v_fma_f32 v25, -v21, v24, v23
	v_fmac_f32_e32 v24, v25, v22
	v_fma_f32 v21, -v21, v24, v23
	v_div_fmas_f32 v21, v21, v22, v24
	v_div_fixup_f32 v4, v21, v4, 1.0
	v_div_scale_f32 v21, s[10:11], v0, v0, 1.0
	v_rcp_f32_e32 v22, v21
	v_exp_f32_e32 v5, v5
	v_add_f32_e32 v1, v1, v19
	v_mul_f32_e32 v1, 0xbfb8aa3b, v1
	v_fma_f32 v23, -v21, v22, 1.0
	v_fmac_f32_e32 v22, v23, v22
	v_div_scale_f32 v23, vcc, 1.0, v0, 1.0
	v_mul_f32_e32 v24, v23, v22
	v_fma_f32 v25, -v21, v24, v23
	v_fmac_f32_e32 v24, v25, v22
	v_fma_f32 v21, -v21, v24, v23
	v_div_fmas_f32 v21, v21, v22, v24
	v_div_fixup_f32 v21, v21, v0, 1.0
	v_mul_f32_e32 v0, v4, v18
	v_mul_f32_e32 v0, 0x3fb8aa3b, v0
	v_exp_f32_e32 v0, v0
	v_add_f32_e32 v5, 1.0, v5
	v_exp_f32_e32 v1, v1
	v_add_f32_e32 v3, v3, v19
	v_fma_f32 v4, -v0, v0, 1.0
	v_max_f32_e32 v4, 0, v4
	v_cmp_gt_f32_e32 vcc, s24, v4
	v_mul_f32_e32 v22, 0x4f800000, v4
	v_add_f32_e32 v1, 1.0, v1
	v_cndmask_b32_e32 v4, v4, v22, vcc
	v_sqrt_f32_e32 v22, v4
	v_mul_f32_e32 v3, 0xbfb8aa3b, v3
	v_exp_f32_e32 v3, v3
	v_add_u32_e32 v23, -1, v22
	v_fma_f32 v24, -v23, v22, v4
	v_cmp_ge_f32_e64 s[42:43], 0, v24
	v_add_u32_e32 v24, 1, v22
	v_add_f32_e32 v3, 1.0, v3
	v_cndmask_b32_e64 v23, v22, v23, s[42:43]
	v_fma_f32 v22, -v24, v22, v4
	v_cmp_lt_f32_e64 s[42:43], 0, v22
	s_nop 1
	v_cndmask_b32_e64 v22, v23, v24, s[42:43]
	v_mul_f32_e32 v23, 0x37800000, v22
	v_cndmask_b32_e32 v22, v22, v23, vcc
	v_cmp_class_f32_e32 vcc, v4, v190
	s_nop 1
	v_cndmask_b32_e32 v4, v22, v4, vcc
	v_mul_f32_e32 v4, v21, v4
	v_add_u32_e32 v21, 0, v16
	ds_read2st64_b32 v[22:23], v21 offset1:2
	v_add_u32_e32 v16, 64, v16
	s_waitcnt lgkmcnt(0)
	v_mul_f32_e32 v4, v22, v4
	v_div_scale_f32 v22, s[10:11], v5, v5, 1.0
	v_rcp_f32_e32 v24, v22
	s_nop 0
	v_fma_f32 v25, -v22, v24, 1.0
	v_fmac_f32_e32 v24, v25, v24
	v_div_scale_f32 v25, vcc, 1.0, v5, 1.0
	v_mul_f32_e32 v26, v25, v24
	v_fma_f32 v27, -v22, v26, v25
	v_fmac_f32_e32 v26, v27, v24
	v_fma_f32 v22, -v22, v26, v25
	v_div_fmas_f32 v22, v22, v24, v26
	v_div_fixup_f32 v5, v22, v5, 1.0
	v_div_scale_f32 v22, s[10:11], v1, v1, 1.0
	v_rcp_f32_e32 v24, v22
	v_mul_f32_e32 v5, v5, v18
	v_mul_f32_e32 v5, 0x3fb8aa3b, v5
	v_exp_f32_e32 v5, v5
	v_fma_f32 v25, -v22, v24, 1.0
	v_fmac_f32_e32 v24, v25, v24
	v_div_scale_f32 v25, vcc, 1.0, v1, 1.0
	v_mul_f32_e32 v26, v25, v24
	v_fma_f32 v27, -v22, v26, v25
	v_fmac_f32_e32 v26, v27, v24
	v_fma_f32 v22, -v22, v26, v25
	v_div_fmas_f32 v22, v22, v24, v26
	v_div_fixup_f32 v1, v22, v1, 1.0
	v_fma_f32 v22, -v5, v5, 1.0
	v_max_f32_e32 v22, 0, v22
	v_cmp_gt_f32_e32 vcc, s24, v22
	v_mul_f32_e32 v24, 0x4f800000, v22
	s_nop 0
	v_cndmask_b32_e32 v22, v22, v24, vcc
	v_sqrt_f32_e32 v24, v22
	s_nop 0
	v_add_u32_e32 v25, -1, v24
	v_fma_f32 v26, -v25, v24, v22
	v_cmp_ge_f32_e64 s[42:43], 0, v26
	v_add_u32_e32 v26, 1, v24
	s_nop 0
	v_cndmask_b32_e64 v25, v24, v25, s[42:43]
	v_fma_f32 v24, -v26, v24, v22
	v_cmp_lt_f32_e64 s[42:43], 0, v24
	s_nop 1
	v_cndmask_b32_e64 v24, v25, v26, s[42:43]
	v_mul_f32_e32 v25, 0x37800000, v24
	v_cndmask_b32_e32 v24, v24, v25, vcc
	v_cmp_class_f32_e32 vcc, v22, v190
	s_nop 1
	v_cndmask_b32_e32 v22, v24, v22, vcc
	v_mul_f32_e32 v1, v1, v22
	v_mul_f32_e32 v1, v23, v1
	ds_write2st64_b32 v21, v0, v5 offset0:128 offset1:130
	ds_write2st64_b32 v21, v4, v1 offset1:2
	v_add_f32_e32 v0, v6, v20
	v_mul_f32_e32 v0, 0xbfb8aa3b, v0
	v_exp_f32_e32 v0, v0
	s_nop 0
	v_add_f32_e32 v0, 1.0, v0
	v_div_scale_f32 v1, s[10:11], v0, v0, 1.0
	v_rcp_f32_e32 v4, v1
	s_nop 0
	v_fma_f32 v5, -v1, v4, 1.0
	v_fmac_f32_e32 v4, v5, v4
	v_div_scale_f32 v5, vcc, 1.0, v0, 1.0
	v_mul_f32_e32 v6, v5, v4
	v_fma_f32 v22, -v1, v6, v5
	v_fmac_f32_e32 v6, v22, v4
	v_fma_f32 v1, -v1, v6, v5
	v_div_fmas_f32 v1, v1, v4, v6
	v_div_fixup_f32 v0, v1, v0, 1.0
	v_add_f32_e32 v1, v2, v19
	v_mul_f32_e32 v1, 0xbfb8aa3b, v1
	v_exp_f32_e32 v1, v1
	v_mul_f32_e32 v0, v0, v18
	v_mul_f32_e32 v0, 0x3fb8aa3b, v0
	v_add_f32_e32 v1, 1.0, v1
	v_div_scale_f32 v2, s[10:11], v1, v1, 1.0
	v_rcp_f32_e32 v4, v2
	s_nop 0
	v_fma_f32 v5, -v2, v4, 1.0
	v_fmac_f32_e32 v4, v5, v4
	v_div_scale_f32 v5, vcc, 1.0, v1, 1.0
	v_mul_f32_e32 v6, v5, v4
	v_fma_f32 v22, -v2, v6, v5
	v_fmac_f32_e32 v6, v22, v4
	v_fma_f32 v2, -v2, v6, v5
	v_div_fmas_f32 v2, v2, v4, v6
	v_div_fixup_f32 v1, v2, v1, 1.0
	v_exp_f32_e32 v2, v0
	s_nop 0
	v_fma_f32 v0, -v2, v2, 1.0
	v_max_f32_e32 v0, 0, v0
	v_cmp_gt_f32_e32 vcc, s24, v0
	v_mul_f32_e32 v4, 0x4f800000, v0
	s_nop 0
	v_cndmask_b32_e32 v0, v0, v4, vcc
	v_sqrt_f32_e32 v4, v0
	s_nop 0
	v_add_u32_e32 v5, -1, v4
	v_fma_f32 v6, -v5, v4, v0
	v_cmp_ge_f32_e64 s[42:43], 0, v6
	v_add_u32_e32 v6, 1, v4
	s_nop 0
	v_cndmask_b32_e64 v5, v4, v5, s[42:43]
	v_fma_f32 v4, -v6, v4, v0
	v_cmp_lt_f32_e64 s[42:43], 0, v4
	s_nop 1
	v_cndmask_b32_e64 v4, v5, v6, s[42:43]
	v_mul_f32_e32 v5, 0x37800000, v4
	v_cndmask_b32_e32 v4, v4, v5, vcc
	v_cmp_class_f32_e32 vcc, v0, v190
	s_nop 1
	v_cndmask_b32_e32 v0, v4, v0, vcc
	v_mul_f32_e32 v4, v1, v0
	ds_read2st64_b32 v[0:1], v21 offset0:4 offset1:6
	s_waitcnt lgkmcnt(0)
	v_mul_f32_e32 v0, v0, v4
	v_add_f32_e32 v4, v7, v20
	v_mul_f32_e32 v4, 0xbfb8aa3b, v4
	v_exp_f32_e32 v4, v4
	s_nop 0
	v_add_f32_e32 v4, 1.0, v4
	v_div_scale_f32 v5, s[10:11], v4, v4, 1.0
	v_rcp_f32_e32 v6, v5
	s_nop 0
	v_fma_f32 v7, -v5, v6, 1.0
	v_fmac_f32_e32 v6, v7, v6
	v_div_scale_f32 v7, vcc, 1.0, v4, 1.0
	v_mul_f32_e32 v20, v7, v6
	v_fma_f32 v22, -v5, v20, v7
	v_fmac_f32_e32 v20, v22, v6
	v_fma_f32 v5, -v5, v20, v7
	v_div_fmas_f32 v5, v5, v6, v20
	v_div_fixup_f32 v4, v5, v4, 1.0
	v_div_scale_f32 v5, s[10:11], v3, v3, 1.0
	v_rcp_f32_e32 v6, v5
	v_mul_f32_e32 v4, v4, v18
	v_mul_f32_e32 v4, 0x3fb8aa3b, v4
	v_exp_f32_e32 v4, v4
	v_fma_f32 v7, -v5, v6, 1.0
	v_fmac_f32_e32 v6, v7, v6
	v_div_scale_f32 v7, vcc, 1.0, v3, 1.0
	v_mul_f32_e32 v19, v7, v6
	v_fma_f32 v20, -v5, v19, v7
	v_fmac_f32_e32 v19, v20, v6
	v_fma_f32 v5, -v5, v19, v7
	v_div_fmas_f32 v5, v5, v6, v19
	v_div_fixup_f32 v3, v5, v3, 1.0
	v_fma_f32 v5, -v4, v4, 1.0
	v_max_f32_e32 v5, 0, v5
	v_cmp_gt_f32_e32 vcc, s24, v5
	v_mul_f32_e32 v6, 0x4f800000, v5
	s_nop 0
	v_cndmask_b32_e32 v5, v5, v6, vcc
	v_sqrt_f32_e32 v6, v5
	s_nop 0
	v_add_u32_e32 v7, -1, v6
	v_fma_f32 v18, -v7, v6, v5
	v_cmp_ge_f32_e64 s[42:43], 0, v18
	v_add_u32_e32 v18, 1, v6
	s_nop 0
	v_cndmask_b32_e64 v7, v6, v7, s[42:43]
	v_fma_f32 v6, -v18, v6, v5
	v_cmp_lt_f32_e64 s[42:43], 0, v6
	s_nop 1
	v_cndmask_b32_e64 v6, v7, v18, s[42:43]
	v_mul_f32_e32 v7, 0x37800000, v6
	v_cndmask_b32_e32 v6, v6, v7, vcc
	v_cmp_class_f32_e32 vcc, v5, v190
	s_nop 1
	v_cndmask_b32_e32 v5, v6, v5, vcc
	v_mul_f32_e32 v3, v3, v5
	v_mul_f32_e32 v1, v1, v3
	ds_write2st64_b32 v21, v2, v4 offset0:132 offset1:134
	ds_write2st64_b32 v21, v0, v1 offset0:4 offset1:6
	s_cbranch_scc0 .LBB0_710
	v_lshlrev_b32_e32 v0, 2, v13
	v_lshl_or_b32 v1, v12, 13, v0
	s_waitcnt lgkmcnt(0)
	s_barrier
	v_add_u32_e32 v2, 0, v1
	ds_read2st64_b32 v[4:5], v2 offset0:128 offset1:130
	ds_read2st64_b32 v[6:7], v2 offset1:2
	v_readlane_b32 s6, v255, 4
	v_mov_b32_e32 v1, 0
	v_cmp_lt_i32_e32 vcc, 0, v12
	s_waitcnt lgkmcnt(0)
	v_fma_f32 v3, 0, v4, v6
	v_fmac_f32_e32 v7, v3, v5
	ds_write2st64_b32 v2, v3, v7 offset1:2
	v_mul_f32_e32 v6, v4, v5
	ds_read2st64_b32 v[4:5], v2 offset0:132 offset1:134
	ds_read2st64_b32 v[14:15], v2 offset0:4 offset1:6
	s_waitcnt lgkmcnt(0)
	v_fma_f32 v3, v7, v4, v14
	v_mul_f32_e32 v4, v6, v4
	v_fmac_f32_e32 v15, v3, v5
	ds_write2st64_b32 v2, v6, v4 offset0:130 offset1:132
	ds_write2st64_b32 v2, v3, v15 offset0:4 offset1:6
	v_mul_f32_e32 v13, v4, v5
	ds_read2st64_b32 v[4:5], v2 offset0:136 offset1:138
	ds_read2st64_b32 v[6:7], v2 offset0:8 offset1:10
	s_waitcnt lgkmcnt(0)
	v_fma_f32 v3, v15, v4, v6
	v_mul_f32_e32 v4, v13, v4
	v_fmac_f32_e32 v7, v3, v5
	ds_write2st64_b32 v2, v13, v4 offset0:134 offset1:136
	ds_write2st64_b32 v2, v3, v7 offset0:8 offset1:10
	v_mul_f32_e32 v6, v4, v5
	ds_read2st64_b32 v[4:5], v2 offset0:140 offset1:142
	ds_read2st64_b32 v[14:15], v2 offset0:12 offset1:14
	s_waitcnt lgkmcnt(0)
	v_fma_f32 v3, v7, v4, v14
	v_mul_f32_e32 v4, v6, v4
	v_fmac_f32_e32 v15, v3, v5
	ds_write2st64_b32 v2, v6, v4 offset0:138 offset1:140
	ds_write2st64_b32 v2, v3, v15 offset0:12 offset1:14
	v_mul_f32_e32 v13, v4, v5
	ds_read2st64_b32 v[4:5], v2 offset0:144 offset1:146
	ds_read2st64_b32 v[6:7], v2 offset0:16 offset1:18
	s_waitcnt lgkmcnt(0)
	v_fma_f32 v3, v15, v4, v6
	v_mul_f32_e32 v4, v13, v4
	v_fmac_f32_e32 v7, v3, v5
	ds_write2st64_b32 v2, v13, v4 offset0:142 offset1:144
	ds_write2st64_b32 v2, v3, v7 offset0:16 offset1:18
	v_mul_f32_e32 v6, v4, v5
	ds_read2st64_b32 v[4:5], v2 offset0:148 offset1:150
	ds_read2st64_b32 v[14:15], v2 offset0:20 offset1:22
	s_waitcnt lgkmcnt(0)
	v_fma_f32 v3, v7, v4, v14
	v_mul_f32_e32 v4, v6, v4
	v_fmac_f32_e32 v15, v3, v5
	ds_write2st64_b32 v2, v6, v4 offset0:146 offset1:148
	ds_write2st64_b32 v2, v3, v15 offset0:20 offset1:22
	v_mul_f32_e32 v13, v4, v5
	ds_read2st64_b32 v[4:5], v2 offset0:152 offset1:154
	ds_read2st64_b32 v[6:7], v2 offset0:24 offset1:26
	s_waitcnt lgkmcnt(0)
	v_fma_f32 v3, v15, v4, v6
	v_mul_f32_e32 v4, v13, v4
	v_fmac_f32_e32 v7, v3, v5
	ds_write2st64_b32 v2, v13, v4 offset0:150 offset1:152
	ds_write2st64_b32 v2, v3, v7 offset0:24 offset1:26
	v_mul_f32_e32 v6, v4, v5
	ds_read2st64_b32 v[4:5], v2 offset0:156 offset1:158
	ds_read2st64_b32 v[14:15], v2 offset0:28 offset1:30
	s_waitcnt lgkmcnt(0)
	v_fma_f32 v3, v7, v4, v14
	v_mul_f32_e32 v4, v6, v4
	v_fmac_f32_e32 v15, v3, v5
	ds_write2st64_b32 v2, v6, v4 offset0:154 offset1:156
	v_mul_f32_e32 v4, v4, v5
	ds_write2st64_b32 v2, v3, v15 offset0:28 offset1:30
	ds_write_b32 v2, v4 offset:40448
	v_lshl_add_u32 v3, v9, 2, s6
	v_and_b32_e32 v5, 0x3fffff80, v9
	ds_write_b32 v3, v4
	v_add_u32_e32 v3, s6, v0
	v_lshl_add_u32 v0, v5, 2, v3
	ds_write_b32 v0, v15 offset:2048
	s_waitcnt lgkmcnt(0)
	s_barrier
	v_mov_b32_e32 v0, 1.0
	s_and_saveexec_b64 s[42:43], vcc
	s_cbranch_execnz .LBB0_753
	s_or_b64 exec, exec, s[42:43]
	v_cmp_lt_i32_e64 s[42:43], 1, v12
	s_and_saveexec_b64 s[58:59], s[42:43]
	s_cbranch_execnz .LBB0_754

.LBB0_735:
	s_or_b64 exec, exec, s[42:43]
	s_movk_i32 s11, 0x180
	v_ashrrev_i32_e32 v17, 6, v16
	v_cmp_gt_i32_e32 vcc, s11, v16
	s_and_saveexec_b64 s[42:43], vcc
	s_cbranch_execz .LBB0_737
	s_mov_b32 s100, 0xbc8102b3
	s_cmp_eq_u32 s10, 0
	s_cselect_b32 s100, 0xbd020aec, s100
	s_mov_b32 s101, 0xbb80402b
	s_cmp_eq_u32 s10, 2
	s_cselect_b32 s101, 0xbc0080ac, s101
	s_cmp_lt_u32 s10, 2
	s_cselect_b32 s100, s100, s101
	v_mov_b32_e32 v5, s100
	s_lshl_b32 s60, s6, 1
	s_movk_i32 s6, 0xc0
	v_lshlrev_b32_e32 v10, 3, v17
	v_ashrrev_i32_e32 v11, 31, v10
	v_mov_b64_e32 v[12:13], s[80:81]
	s_nop 0
	v_mov_b64_e32 v[0:1], s[48:49]
	v_mad_u64_u32 v[0:1], s[10:11], v4, s13, v[0:1]
	v_mad_i32_i24 v1, s53, v204, v1
	v_lshl_add_u64 v[0:1], v[0:1], 0, s[60:61]
	v_lshl_add_u64 v[6:7], v[10:11], 1, v[0:1]
	global_load_dwordx4 v[0:3], v[6:7], off offset:768
	s_nop 0
	global_load_dwordx4 v[6:9], v[6:7], off offset:864
	s_waitcnt vmcnt(0)
	v_lshlrev_b32_e32 v25, 16, v0
	v_and_b32_e32 v26, 0xffff0000, v0
	v_xor_b32_e32 v0, 63, v18
	v_cvt_f32_ubyte0_e32 v0, v0
	v_mul_f32_e32 v0, v5, v0
	v_mul_f32_e32 v0, 0x3fb8aa3b, v0
	v_lshlrev_b32_e32 v27, 16, v1
	v_and_b32_e32 v28, 0xffff0000, v1
	v_exp_f32_e32 v22, v0
	v_mov_b64_e32 v[0:1], s[84:85]
	v_mad_u64_u32 v[0:1], s[10:11], v4, s6, v[0:1]
	v_mad_u64_u32 v[4:5], s[10:11], v4, s6, v[12:13]
	v_lshlrev_b32_e32 v30, 16, v6
	v_and_b32_e32 v31, 0xffff0000, v6
	v_lshlrev_b32_e32 v32, 16, v7
	v_and_b32_e32 v33, 0xffff0000, v7
	v_mad_i32_i24 v1, s53, v205, v1
	v_lshlrev_b64 v[6:7], 2, v[10:11]
	v_mad_i32_i24 v5, s53, v205, v5
	v_lshlrev_b32_e32 v34, 16, v8
	v_and_b32_e32 v35, 0xffff0000, v8
	v_lshlrev_b32_e32 v23, 16, v9
	v_and_b32_e32 v20, 0xffff0000, v9
	v_lshl_add_u64 v[8:9], v[0:1], 0, v[6:7]
	v_lshl_add_u64 v[12:13], v[4:5], 0, v[6:7]
	v_lshlrev_b32_e32 v29, 16, v2
	v_and_b32_e32 v24, 0xffff0000, v2
	v_lshlrev_b32_e32 v21, 16, v3
	v_and_b32_e32 v19, 0xffff0000, v3
	global_load_dwordx4 v[0:3], v[8:9], off offset:16
	s_nop 0
	global_load_dwordx4 v[8:11], v[8:9], off
	s_nop 0
	global_load_dwordx4 v[4:7], v[12:13], off offset:16
	s_nop 0
	global_load_dwordx4 v[12:15], v[12:13], off
	s_movk_i32 s6, 0x480
	v_lshlrev_b32_e32 v18, 1, v18
	v_mul_lo_u32 v37, v17, s6
	v_add3_u32 v18, 0, v18, v37
	s_waitcnt vmcnt(0)
	v_mul_f32_e32 v36, v12, v30
	v_mul_f32_e32 v12, v12, v25
	v_fmac_f32_e32 v12, v8, v30
	v_fma_f32 v36, v8, v25, -v36
	v_mul_f32_e32 v8, v22, v12
	v_cvt_pk_bf16_f32 v8, v8, s0
	ds_write_b16 v18, v8 offset:31488
	v_mul_f32_e32 v8, v13, v31
	v_fma_f32 v8, v9, v26, -v8
	v_mul_f32_e32 v8, v22, v8
	v_cvt_pk_bf16_f32 v8, v8, s0
	ds_write_b16 v18, v8 offset:24720
	v_mul_f32_e32 v8, v13, v26
	v_fmac_f32_e32 v8, v9, v31
	v_mul_f32_e32 v8, v22, v8
	v_cvt_pk_bf16_f32 v8, v8, s0
	ds_write_b16 v18, v8 offset:31632
	v_mul_f32_e32 v8, v14, v32
	v_fma_f32 v8, v10, v27, -v8
	v_mul_f32_e32 v8, v22, v8
	v_cvt_pk_bf16_f32 v8, v8, s0
	ds_write_b16 v18, v8 offset:24864
	v_mul_f32_e32 v8, v14, v27
	v_fmac_f32_e32 v8, v10, v32
	v_mul_f32_e32 v8, v22, v8
	v_cvt_pk_bf16_f32 v8, v8, s0
	ds_write_b16 v18, v8 offset:31776
	v_mul_f32_e32 v8, v15, v33
	v_fma_f32 v8, v11, v28, -v8
	v_mul_f32_e32 v8, v22, v8
	v_cvt_pk_bf16_f32 v8, v8, s0
	ds_write_b16 v18, v8 offset:25008
	v_mul_f32_e32 v8, v15, v28
	v_fmac_f32_e32 v8, v11, v33
	v_mul_f32_e32 v8, v22, v8
	v_cvt_pk_bf16_f32 v8, v8, s0
	ds_write_b16 v18, v8 offset:31920
	v_mul_f32_e32 v8, v4, v34
	v_mul_f32_e32 v4, v4, v29
	v_fmac_f32_e32 v4, v0, v34
	v_fma_f32 v8, v0, v29, -v8
	v_mul_f32_e32 v0, v22, v4
	v_cvt_pk_bf16_f32 v0, v0, s0
	ds_write_b16 v18, v0 offset:32064
	v_mul_f32_e32 v0, v5, v35
	v_fma_f32 v0, v1, v24, -v0
	v_mul_f32_e32 v0, v22, v0
	v_cvt_pk_bf16_f32 v0, v0, s0
	ds_write_b16 v18, v0 offset:25296
	v_mul_f32_e32 v0, v5, v24
	v_fmac_f32_e32 v0, v1, v35
	v_mul_f32_e32 v0, v22, v0
	v_cvt_pk_bf16_f32 v0, v0, s0
	ds_write_b16 v18, v0 offset:32208
	v_mul_f32_e32 v0, v6, v23
	v_fma_f32 v0, v2, v21, -v0
	v_mul_f32_e32 v0, v22, v0
	v_cvt_pk_bf16_f32 v0, v0, s0
	ds_write_b16 v18, v0 offset:25440
	v_mul_f32_e32 v0, v6, v21
	v_fmac_f32_e32 v0, v2, v23
	v_mul_f32_e32 v0, v22, v0
	v_cvt_pk_bf16_f32 v0, v0, s0
	ds_write_b16 v18, v0 offset:32352
	v_mul_f32_e32 v0, v7, v20
	v_fma_f32 v0, v3, v19, -v0
	v_mul_f32_e32 v0, v22, v0
	v_cvt_pk_bf16_f32 v0, v0, s0
	ds_write_b16 v18, v0 offset:25584
	v_mul_f32_e32 v0, v7, v19
	v_fmac_f32_e32 v0, v3, v20
	v_mul_f32_e32 v36, v22, v36
	v_mul_f32_e32 v8, v22, v8
	v_mul_f32_e32 v0, v22, v0
	v_cvt_pk_bf16_f32 v36, v36, s0
	v_cvt_pk_bf16_f32 v8, v8, s0
	v_cvt_pk_bf16_f32 v0, v0, s0
	ds_write_b16 v18, v36 offset:24576
	ds_write_b16 v18, v8 offset:25152
	ds_write_b16 v18, v0 offset:32496
